# GEMM3 second round split by rows between two workgroups; w_out conversion moved to the idle tail of GEMM1; rwkv_post on workgroups 32+
# baseline (speedup 1.0000x reference)
.Ltr_ret1:
	s_sub_i32 s0, s2, 40
	v_lshl_add_u32 v92, s0, 3, v179
	s_movk_i32 s99, 0x1ff
	s_mov_b32 s3, 40
	s_mov_b32 s98, 4
	s_branch .Ltr_late_entry

.LBB0_994:
	s_lshl_b32 s5, s5, 5
	s_mov_b64 s[22:23], 0x80
	s_and_b32 s5, s5, 0x60
	s_add_i32 m0, s79, 0x18000
	v_lshl_add_u64 v[8:9], v[8:9], 0, s[22:23]
	s_lshl_b32 s12, s1, 13
	s_lshl_b32 s13, s5, 7
	s_waitcnt vmcnt(2)
	s_barrier
	global_load_lds_dwordx4 v[8:9], off
	v_lshl_add_u64 v[6:7], v[6:7], 0, s[22:23]
	s_add_i32 m0, s79, 0x1a000
	s_add_i32 s83, s79, 0x8000
	s_add_i32 s84, s79, 0xa000
	global_load_lds_dwordx4 v[6:7], off
	v_lshl_add_u64 v[2:3], v[2:3], 0, s[22:23]
	s_mov_b32 m0, s83
	s_add_u32 s10, s6, 0x10080
	global_load_lds_dwordx4 v[2:3], off
	v_lshl_add_u64 v[2:3], v[4:5], 0, s[22:23]
	s_mov_b32 m0, s84
	s_addc_u32 s11, s7, 0
	global_load_lds_dwordx4 v[2:3], off
	s_add_i32 m0, s79, 0x1c000
	v_lshl_add_u64 v[2:3], s[10:11], 0, v[150:151]
	global_load_lds_dwordx4 v[2:3], off
	v_lshl_add_u64 v[2:3], s[10:11], 0, v[146:147]
	s_add_i32 m0, s79, 0x1e000
	s_cmpk_lt_u32 s0, 0x100
	global_load_lds_dwordx4 v[2:3], off
	s_cselect_b64 s[24:25], -1, 0
	s_ashr_i32 s86, s48, 31
	s_add_u32 s26, s46, 0x1dd00000
	s_addc_u32 s27, s47, 0
	v_and_b32_e32 v2, 15, v178
	s_add_u32 s28, s46, 0x1bb00000
	v_lshl_or_b32 v1, s1, 6, v2
	v_lshlrev_b32_e32 v3, 1, v10
	v_lshlrev_b32_e32 v4, 2, v178
	v_lshlrev_b32_e32 v5, 6, v178
	s_movk_i32 s1, 0x3c0
	s_addc_u32 s29, s47, 0
	v_lshl_or_b32 v2, v2, 6, v3
	v_and_b32_e32 v4, 32, v4
	v_and_or_b32 v3, v5, s1, v3
	s_waitcnt vmcnt(6)
	s_add_u32 s30, s46, 0x3000000
	v_bitop3_b32 v2, v2, s12, v4 bitop3:0xde
	v_bitop3_b32 v174, s13, v3, v4 bitop3:0xf6
	s_addc_u32 s31, s47, 0
	s_add_i32 s88, 0, 0x10000
	s_add_i32 s89, 0, 0x14000
	s_sext_i32_i8 s94, s4
	s_mov_b32 s85, 0
	s_mov_b32 s87, s48
	v_or_b32_e32 v175, s5, v10
	v_mov_b64_e32 v[156:157], 0x330
	v_mov_b64_e32 v[158:159], 0x32f
	v_add_u32_e32 v176, s88, v174
	v_add_u32_e32 v177, s89, v174
	v_add_u32_e32 v180, 0, v2
	s_mov_b64 s[34:35], 0x40000
	s_mov_b32 s90, 0x40000
	s_mov_b64 s[36:37], 0x48000
	s_mov_b32 s91, 0x48000
	s_mov_b64 s[38:39], 0x50000
	s_mov_b32 s92, 0x50000
	s_mov_b64 s[40:41], 0x58000
	s_mov_b32 s93, 0x58000
	s_barrier
	s_branch .LBB0_997
.Ltr_tramp4:
	s_branch .Ltr_ret1b
.LBB0_995:
	s_mov_b64 s[4:5], 0

.LBB0_1445:
.LBB0_1446:
	s_cmp_lt_i32 s50, 8
	s_cselect_b64 s[0:1], -1, 0
	s_and_b64 s[8:9], s[0:1], s[4:5]
	s_andn2_b64 vcc, exec, s[8:9]
	s_cbranch_vccnz .LBB0_1828
	s_mov_b32 s101, 0
	v_readfirstlane_b32 s99, v179
	s_lshr_b32 s99, s99, 2
	s_add_u32 s12, s46, 0x5200000
	s_addc_u32 s13, s47, 0
	s_add_u32 s10, s46, 0x1600000
	s_addc_u32 s11, s47, 0
	v_readfirstlane_b32 s0, v178
	s_cmpk_gt_i32 s2, 0x10f
	v_lshlrev_b32_e32 v1, 4, v178
	s_waitcnt vmcnt(0)
	s_barrier
	s_cbranch_scc1 .LBB0_1465
	v_lshrrev_b32_e32 v2, 5, v178
	v_lshrrev_b32_e32 v4, 1, v178
	v_and_b32_e32 v2, 4, v2
	v_bfe_u32 v3, v178, 2, 2
	v_and_b32_e32 v10, 24, v4
	v_or3_b32 v2, v2, v3, v10
	v_add_u32_e32 v3, 0x2000, v1
	v_and_b32_e32 v5, 32, v178
	v_lshrrev_b32_e32 v3, 7, v3
	s_movk_i32 s4, 0xe0
	v_bitop3_b32 v11, v1, v5, 48 bitop3:0x6c
	v_and_b32_e32 v12, 64, v178
	v_and_or_b32 v4, v3, s4, v2
	v_or_b32_e32 v5, v11, v12
	v_lshl_or_b32 v134, v4, 12, v5
	v_bfe_u32 v4, v178, 2, 4
	s_movk_i32 s4, 0xf0
	v_and_or_b32 v3, v3, s4, v4
	v_mul_u32_u24_e32 v13, 0x5200, v3
	v_lshrrev_b32_e32 v3, 3, v178
	s_movk_i32 s4, 0x60
	v_and_or_b32 v2, v3, s4, v2
	s_movk_i32 s4, 0x70
	s_ashr_i32 s36, s2, 31
	v_lshl_or_b32 v138, v2, 12, v5
	v_and_or_b32 v2, v3, s4, v4
	s_lshr_b32 s4, s36, 29
	s_add_i32 s4, s2, s4
	s_lshr_b32 s5, s0, 6
	s_ashr_i32 s6, s4, 3
	s_and_b32 s4, s4, -8
	s_lshr_b32 s1, s0, 8
	s_lshl_b32 s3, s5, 10
	s_sub_i32 s4, s2, s4
	s_cmp_lt_i32 s4, 0
	s_cselect_b32 s7, 35, 34
	s_mul_i32 s4, s4, s7
	s_add_i32 s4, s4, s6
	s_ashr_i32 s6, s4, 31
	s_lshr_b32 s6, s6, 27
	s_add_i32 s6, s4, s6
	s_ashr_i32 s6, s6, 5
	s_lshl_b32 s14, s6, 3
	s_sub_i32 s7, 0x44, s14
	s_lshl_b32 s6, s6, 5
	s_min_u32 s15, s7, 8
	s_sub_i32 s16, s4, s6
	s_sext_i32_i8 s4, s16
	v_cvt_f32_ubyte0_e32 v3, s15
	v_mul_u32_u24_e32 v14, 0x5200, v2
	v_cvt_f32_i32_e32 v2, s4
	v_rcp_iflag_f32_e32 v4, v3
	s_ashr_i32 s4, s4, 30
	s_or_b32 s4, s4, 1
	v_or_b32_e32 v140, v5, v14
	v_mul_f32_e32 v4, v2, v4
	v_trunc_f32_e32 v4, v4
	v_fma_f32 v2, -v4, v3, v2
	v_cvt_i32_f32_e32 v4, v4
	v_cmp_ge_f32_e64 s[6:7], |v2|, v3
	s_and_b64 s[6:7], s[6:7], exec
	s_cselect_b32 s4, s4, 0
	v_readfirstlane_b32 s6, v4
	s_add_i32 s4, s6, s4
	s_mul_i32 s6, s4, s15
	s_sub_i32 s6, s16, s6
	s_sext_i32_i8 s6, s6
	s_add_i32 s62, s14, s6
	s_bfe_i64 s[6:7], s[4:5], 0x80000
	s_lshl_b64 s[6:7], s[6:7], 20
	s_add_u32 s30, s10, s6
	s_addc_u32 s31, s11, s7
	s_add_i32 s37, s3, 0
	s_add_i32 m0, s37, 0x10000
	s_mul_i32 s15, s62, 0x520000
	global_load_lds_dwordx4 v138, s[30:31]
	s_add_i32 m0, s37, 0x12000
	s_add_u32 s6, s30, 0x80000
	global_load_lds_dwordx4 v134, s[30:31]
	s_addc_u32 s7, s31, 0
	s_add_i32 m0, s37, 0x14000
	s_mul_hi_i32 s14, s62, 0x520000
	global_load_lds_dwordx4 v138, s[6:7]
	s_add_i32 m0, s37, 0x16000
	s_add_u32 s34, s12, s15
	s_addc_u32 s35, s13, s14
	s_add_i32 s38, s37, 0x2000
	global_load_lds_dwordx4 v134, s[6:7]
	s_mov_b32 m0, s37
	s_add_u32 s6, s34, 0x290000
	v_or_b32_e32 v136, v13, v5
	global_load_lds_dwordx4 v140, s[34:35]
	s_mov_b32 m0, s38
	s_addc_u32 s7, s35, 0
	s_add_i32 s39, s37, 0x4000
	global_load_lds_dwordx4 v136, s[34:35]
	s_mov_b32 m0, s39
	s_add_i32 s40, s37, 0x6000
	global_load_lds_dwordx4 v140, s[6:7]
	s_mov_b32 m0, s40
	v_mov_b32_e32 v139, 0
	global_load_lds_dwordx4 v136, s[6:7]
	v_mov_b32_e32 v135, v139
	v_mov_b32_e32 v141, v139
	v_mov_b32_e32 v137, v139
	s_cmp_eq_u32 s1, 1
	s_movk_i32 s41, 0x5200
	s_mov_b32 s42, 0
	v_lshl_add_u64 v[8:9], s[30:31], 0, v[138:139]
	v_lshl_add_u64 v[6:7], s[30:31], 0, v[134:135]
	v_lshl_add_u64 v[2:3], s[34:35], 0, v[140:141]
	s_cselect_b64 s[14:15], -1, 0
	s_cmp_lg_u32 s1, 1
	v_lshl_add_u64 v[4:5], s[34:35], 0, v[136:137]
	s_cbranch_scc1 .LBB0_1450
	s_barrier

.LBB0_1453:
	s_add_i32 s42, s42, 1
	s_mul_i32 s0, s42, s57
	s_mul_hi_u32 s1, s42, s58
	s_add_i32 s1, s1, s0
	s_mul_i32 s0, s42, s58
	s_add_u32 s4, s0, s2
	s_addc_u32 s5, s1, s36
	s_mov_b32 s100, s101
	s_mov_b32 s101, 0
	s_cmp_eq_u32 s48, 0x100
	s_cbranch_scc0 .Lsplit7_done
	s_cmp_eq_u32 s42, 1
	s_cbranch_scc0 .Lsplit7_done
	s_cmp_lt_u32 s2, 16
	s_cbranch_scc0 .Lsplit7_helper
	s_mov_b32 s101, 2
	s_branch .Lsplit7_done
.Lsplit7_helper:
	s_cmp_lt_u32 s2, 32
	s_cbranch_scc0 .Lsplit7_done
	s_sub_u32 s4, s4, 16
	s_mov_b32 s101, 1
.Lsplit7_done:
	s_sub_u32 s98, s100, 1
	v_cmp_gt_i64_e32 vcc, s[4:5], v[148:149]
	v_cmp_lt_i64_e64 s[6:7], s[4:5], v[146:147]
	s_cbranch_vccnz .LBB0_1455
	s_ashr_i32 s0, s4, 31
	s_lshr_b32 s0, s0, 29
	s_add_i32 s0, s4, s0
	s_ashr_i32 s1, s0, 3
	s_and_b32 s0, s0, -8
	s_sub_i32 s0, s4, s0
	s_cmp_lt_i32 s0, 0
	s_cselect_b32 s4, 35, 34
	s_mul_i32 s0, s0, s4
	s_add_i32 s0, s0, s1
	s_ashr_i32 s1, s0, 31
	s_lshr_b32 s1, s1, 27
	s_add_i32 s1, s0, s1
	s_ashr_i32 s4, s1, 5
	s_lshl_b32 s4, s4, 3
	s_sub_i32 s5, 0x44, s4
	s_min_i32 s5, s5, 8
	s_abs_i32 s24, s5
	v_cvt_f32_u32_e32 v2, s24
	s_sub_i32 s26, 0, s24
	s_andn2_b32 s1, s1, 31
	s_sub_i32 s0, s0, s1
	v_rcp_iflag_f32_e32 v2, v2
	s_abs_i32 s1, s0
	s_xor_b32 s25, s0, s5
	s_ashr_i32 s25, s25, 31
	v_mul_f32_e32 v2, 0x4f7ffffe, v2
	v_cvt_u32_f32_e32 v2, v2
	s_nop 0
	v_readfirstlane_b32 s27, v2
	s_mul_i32 s26, s26, s27
	s_mul_hi_u32 s26, s27, s26
	s_add_i32 s27, s27, s26
	s_mul_hi_u32 s26, s1, s27
	s_mul_i32 s27, s26, s24
	s_sub_i32 s1, s1, s27
	s_add_i32 s28, s26, 1
	s_sub_i32 s27, s1, s24
	s_cmp_ge_u32 s1, s24
	s_cselect_b32 s26, s28, s26
	s_cselect_b32 s1, s27, s1
	s_add_i32 s27, s26, 1
	s_cmp_ge_u32 s1, s24
	s_cselect_b32 s1, s27, s26
	s_xor_b32 s1, s1, s25
	s_sub_i32 s24, s1, s25
	s_mul_i32 s1, s24, s5
	s_sub_i32 s0, s0, s1
	s_add_i32 s61, s4, s0

.LBB0_1458:
	ds_read_b128 v[130:133], v163
	ds_read_b128 v[150:153], v163 offset:1024
	ds_read_b128 v[154:157], v163 offset:2048
	ds_read_b128 v[166:169], v163 offset:3072
	ds_read_b128 v[170:173], v164
	ds_read_b128 v[174:177], v164 offset:1024
	ds_read_b128 v[180:183], v164 offset:2048
	ds_read_b128 v[184:187], v164 offset:3072
	s_add_u32 s0, s6, 0xffd70080
	s_addc_u32 s1, s7, -1
	s_cmp_eq_u32 s67, 28
	s_cselect_b32 s35, s27, s1
	s_cselect_b32 s34, s26, s0
	s_cselect_b32 s31, s25, s66
	s_cselect_b32 s30, s64, s65
	v_lshl_add_u64 v[158:159], s[6:7], 0, v[142:143]
	s_add_i32 m0, s37, 0xc000
	ds_read_b128 v[188:191], v165
	ds_read_b128 v[192:195], v165 offset:1024
	ds_read_b128 v[196:199], v165 offset:2048
	ds_read_b128 v[200:203], v165 offset:3072
	ds_read_b128 v[204:207], v165 offset:4096
	ds_read_b128 v[208:211], v165 offset:5120
	ds_read_b128 v[212:215], v165 offset:6144
	ds_read_b128 v[216:219], v165 offset:7168
	global_load_lds_dwordx4 v[158:159], off
	v_lshl_add_u64 v[158:159], s[6:7], 0, v[144:145]
	s_add_i32 m0, s37, 0xe000
	s_nop 0
	global_load_lds_dwordx4 v[158:159], off
	s_waitcnt vmcnt(8)
	s_waitcnt lgkmcnt(0)
	s_barrier
	s_cmp_eq_u32 s99, s98
	s_cbranch_scc1 .Lsplit7_mma0
	s_setprio 1
	s_waitcnt lgkmcnt(0)
	v_mfma_f32_16x16x32_bf16 v[126:129], v[130:133], v[188:191], v[126:129]
	v_mfma_f32_16x16x32_bf16 v[122:125], v[154:157], v[188:191], v[122:125]
	v_mfma_f32_16x16x32_bf16 v[118:121], v[130:133], v[196:199], v[118:121]
	v_mfma_f32_16x16x32_bf16 v[110:113], v[154:157], v[196:199], v[110:113]
	v_mfma_f32_16x16x32_bf16 v[94:97], v[130:133], v[204:207], v[94:97]
	v_mfma_f32_16x16x32_bf16 v[90:93], v[154:157], v[204:207], v[90:93]
	v_mfma_f32_16x16x32_bf16 v[78:81], v[130:133], v[212:215], v[78:81]
	v_mfma_f32_16x16x32_bf16 v[74:77], v[154:157], v[212:215], v[74:77]
	v_mfma_f32_16x16x32_bf16 v[126:129], v[150:153], v[192:195], v[126:129]
	v_mfma_f32_16x16x32_bf16 v[122:125], v[166:169], v[192:195], v[122:125]
	v_mfma_f32_16x16x32_bf16 v[118:121], v[150:153], v[200:203], v[118:121]
	v_mfma_f32_16x16x32_bf16 v[110:113], v[166:169], v[200:203], v[110:113]
	v_mfma_f32_16x16x32_bf16 v[94:97], v[150:153], v[208:211], v[94:97]
	v_mfma_f32_16x16x32_bf16 v[90:93], v[166:169], v[208:211], v[90:93]
	v_mfma_f32_16x16x32_bf16 v[78:81], v[150:153], v[216:219], v[78:81]
	v_mfma_f32_16x16x32_bf16 v[74:77], v[166:169], v[216:219], v[74:77]
	s_setprio 0
	s_setprio 1
	v_mfma_f32_16x16x32_bf16 v[114:117], v[170:173], v[188:191], v[114:117]
	v_mfma_f32_16x16x32_bf16 v[106:109], v[180:183], v[188:191], v[106:109]
	v_mfma_f32_16x16x32_bf16 v[102:105], v[170:173], v[196:199], v[102:105]
	v_mfma_f32_16x16x32_bf16 v[98:101], v[180:183], v[196:199], v[98:101]
	v_mfma_f32_16x16x32_bf16 v[86:89], v[170:173], v[204:207], v[86:89]
	v_mfma_f32_16x16x32_bf16 v[82:85], v[180:183], v[204:207], v[82:85]
	v_mfma_f32_16x16x32_bf16 v[70:73], v[170:173], v[212:215], v[70:73]
	v_mfma_f32_16x16x32_bf16 v[66:69], v[180:183], v[212:215], v[66:69]
	v_mfma_f32_16x16x32_bf16 v[114:117], v[174:177], v[192:195], v[114:117]
	v_mfma_f32_16x16x32_bf16 v[106:109], v[184:187], v[192:195], v[106:109]
	v_mfma_f32_16x16x32_bf16 v[102:105], v[174:177], v[200:203], v[102:105]
	v_mfma_f32_16x16x32_bf16 v[98:101], v[184:187], v[200:203], v[98:101]
	v_mfma_f32_16x16x32_bf16 v[86:89], v[174:177], v[208:211], v[86:89]
	v_mfma_f32_16x16x32_bf16 v[82:85], v[184:187], v[208:211], v[82:85]
	v_mfma_f32_16x16x32_bf16 v[70:73], v[174:177], v[216:219], v[70:73]
	v_mfma_f32_16x16x32_bf16 v[66:69], v[184:187], v[216:219], v[66:69]
	s_setprio 0
.Lsplit7_mma0:
	s_barrier
	s_add_i32 s0, s59, s3
	v_lshl_add_u64 v[158:159], s[30:31], 0, v[138:139]
	s_mov_b32 m0, s0
	ds_read_b128 v[188:191], v165 offset:16384
	ds_read_b128 v[192:195], v165 offset:17408
	ds_read_b128 v[196:199], v165 offset:18432
	ds_read_b128 v[200:203], v165 offset:19456
	ds_read_b128 v[204:207], v165 offset:20480
	ds_read_b128 v[208:211], v165 offset:21504
	ds_read_b128 v[212:215], v165 offset:22528
	ds_read_b128 v[216:219], v165 offset:23552
	global_load_lds_dwordx4 v[158:159], off
	s_add_i32 m0, s0, 0x2000
	s_add_u32 s0, s30, 0x80000
	v_lshl_add_u64 v[220:221], s[30:31], 0, v[134:135]
	s_addc_u32 s1, s31, 0
	s_add_i32 s33, s60, s3
	global_load_lds_dwordx4 v[220:221], off
	v_lshl_add_u64 v[222:223], s[0:1], 0, v[138:139]
	s_mov_b32 m0, s33
	v_lshl_add_u64 v[224:225], s[34:35], 0, v[136:137]
	global_load_lds_dwordx4 v[222:223], off
	v_lshl_add_u64 v[222:223], s[0:1], 0, v[134:135]
	s_add_i32 m0, s33, 0x2000
	s_nop 0
	global_load_lds_dwordx4 v[222:223], off
	v_lshl_add_u64 v[222:223], s[34:35], 0, v[140:141]
	s_mov_b32 m0, s37
	s_nop 0
	global_load_lds_dwordx4 v[222:223], off
	s_mov_b32 m0, s38
	s_nop 0
	global_load_lds_dwordx4 v[224:225], off
	s_waitcnt vmcnt(8)
	s_waitcnt lgkmcnt(0)
	s_barrier
	s_cmp_eq_u32 s99, s98
	s_cbranch_scc1 .Lsplit7_mma1
	s_setprio 1
	s_waitcnt lgkmcnt(0)
	v_mfma_f32_16x16x32_bf16 v[62:65], v[130:133], v[188:191], v[62:65]
	v_mfma_f32_16x16x32_bf16 v[58:61], v[154:157], v[188:191], v[58:61]
	v_mfma_f32_16x16x32_bf16 v[46:49], v[130:133], v[196:199], v[46:49]
	v_mfma_f32_16x16x32_bf16 v[42:45], v[154:157], v[196:199], v[42:45]
	v_mfma_f32_16x16x32_bf16 v[30:33], v[130:133], v[204:207], v[30:33]
	v_mfma_f32_16x16x32_bf16 v[26:29], v[154:157], v[204:207], v[26:29]
	v_mfma_f32_16x16x32_bf16 v[14:17], v[130:133], v[212:215], v[14:17]
	v_mfma_f32_16x16x32_bf16 v[10:13], v[154:157], v[212:215], v[10:13]
	v_mfma_f32_16x16x32_bf16 v[62:65], v[150:153], v[192:195], v[62:65]
	v_mfma_f32_16x16x32_bf16 v[58:61], v[166:169], v[192:195], v[58:61]
	v_mfma_f32_16x16x32_bf16 v[46:49], v[150:153], v[200:203], v[46:49]
	v_mfma_f32_16x16x32_bf16 v[42:45], v[166:169], v[200:203], v[42:45]
	v_mfma_f32_16x16x32_bf16 v[30:33], v[150:153], v[208:211], v[30:33]
	v_mfma_f32_16x16x32_bf16 v[26:29], v[166:169], v[208:211], v[26:29]
	v_mfma_f32_16x16x32_bf16 v[14:17], v[150:153], v[216:219], v[14:17]
	v_mfma_f32_16x16x32_bf16 v[10:13], v[166:169], v[216:219], v[10:13]
	s_setprio 0
	s_setprio 1
	v_mfma_f32_16x16x32_bf16 v[54:57], v[170:173], v[188:191], v[54:57]
	v_mfma_f32_16x16x32_bf16 v[50:53], v[180:183], v[188:191], v[50:53]
	v_mfma_f32_16x16x32_bf16 v[38:41], v[170:173], v[196:199], v[38:41]
	v_mfma_f32_16x16x32_bf16 v[34:37], v[180:183], v[196:199], v[34:37]
	v_mfma_f32_16x16x32_bf16 v[22:25], v[170:173], v[204:207], v[22:25]
	v_mfma_f32_16x16x32_bf16 v[18:21], v[180:183], v[204:207], v[18:21]
	v_mfma_f32_16x16x32_bf16 v[6:9], v[170:173], v[212:215], v[6:9]
	v_mfma_f32_16x16x32_bf16 v[2:5], v[180:183], v[212:215], v[2:5]
	v_mfma_f32_16x16x32_bf16 v[54:57], v[174:177], v[192:195], v[54:57]
	v_mfma_f32_16x16x32_bf16 v[50:53], v[184:187], v[192:195], v[50:53]
	v_mfma_f32_16x16x32_bf16 v[38:41], v[174:177], v[200:203], v[38:41]
	v_mfma_f32_16x16x32_bf16 v[34:37], v[184:187], v[200:203], v[34:37]
	v_mfma_f32_16x16x32_bf16 v[22:25], v[174:177], v[208:211], v[22:25]
	v_mfma_f32_16x16x32_bf16 v[18:21], v[184:187], v[208:211], v[18:21]
	v_mfma_f32_16x16x32_bf16 v[6:9], v[174:177], v[216:219], v[6:9]
	v_mfma_f32_16x16x32_bf16 v[2:5], v[184:187], v[216:219], v[2:5]
	s_setprio 0
.Lsplit7_mma1:
	s_barrier
	s_add_i32 s33, 0, 0x18000
	s_add_i32 s52, 0, 0x1c000
	v_add_u32_e32 v166, s33, v161
	v_add_u32_e32 v184, s52, v161
	ds_read_b128 v[130:133], v166
	ds_read_b128 v[150:153], v166 offset:1024
	ds_read_b128 v[154:157], v166 offset:2048
	ds_read_b128 v[166:169], v166 offset:3072
	ds_read_b128 v[170:173], v184
	ds_read_b128 v[174:177], v184 offset:1024
	ds_read_b128 v[180:183], v184 offset:2048
	ds_read_b128 v[184:187], v184 offset:3072
	s_add_u32 s0, s34, 0x290000
	s_addc_u32 s1, s35, 0
	s_mov_b32 m0, s39
	v_lshl_add_u64 v[226:227], s[0:1], 0, v[140:141]
	ds_read_b128 v[188:191], v165 offset:32768
	ds_read_b128 v[192:195], v165 offset:33792
	ds_read_b128 v[196:199], v165 offset:34816
	ds_read_b128 v[200:203], v165 offset:35840
	ds_read_b128 v[204:207], v165 offset:36864
	ds_read_b128 v[208:211], v165 offset:37888
	ds_read_b128 v[212:215], v165 offset:38912
	ds_read_b128 v[216:219], v165 offset:39936
	global_load_lds_dwordx4 v[226:227], off
	v_lshl_add_u64 v[226:227], s[0:1], 0, v[136:137]
	s_mov_b32 m0, s40
	s_nop 0
	global_load_lds_dwordx4 v[226:227], off
	s_waitcnt vmcnt(8)
	s_waitcnt lgkmcnt(0)
	s_barrier
	s_cmp_eq_u32 s99, s98
	s_cbranch_scc1 .Lsplit7_mma2
	s_setprio 1
	s_waitcnt lgkmcnt(0)
	v_mfma_f32_16x16x32_bf16 v[126:129], v[130:133], v[188:191], v[126:129]
	v_mfma_f32_16x16x32_bf16 v[122:125], v[154:157], v[188:191], v[122:125]
	v_mfma_f32_16x16x32_bf16 v[118:121], v[130:133], v[196:199], v[118:121]
	v_mfma_f32_16x16x32_bf16 v[110:113], v[154:157], v[196:199], v[110:113]
	v_mfma_f32_16x16x32_bf16 v[94:97], v[130:133], v[204:207], v[94:97]
	v_mfma_f32_16x16x32_bf16 v[90:93], v[154:157], v[204:207], v[90:93]
	v_mfma_f32_16x16x32_bf16 v[78:81], v[130:133], v[212:215], v[78:81]
	v_mfma_f32_16x16x32_bf16 v[74:77], v[154:157], v[212:215], v[74:77]
	v_mfma_f32_16x16x32_bf16 v[126:129], v[150:153], v[192:195], v[126:129]
	v_mfma_f32_16x16x32_bf16 v[122:125], v[166:169], v[192:195], v[122:125]
	v_mfma_f32_16x16x32_bf16 v[118:121], v[150:153], v[200:203], v[118:121]
	v_mfma_f32_16x16x32_bf16 v[110:113], v[166:169], v[200:203], v[110:113]
	v_mfma_f32_16x16x32_bf16 v[94:97], v[150:153], v[208:211], v[94:97]
	v_mfma_f32_16x16x32_bf16 v[90:93], v[166:169], v[208:211], v[90:93]
	v_mfma_f32_16x16x32_bf16 v[78:81], v[150:153], v[216:219], v[78:81]
	v_mfma_f32_16x16x32_bf16 v[74:77], v[166:169], v[216:219], v[74:77]
	s_setprio 0
	s_setprio 1
	v_mfma_f32_16x16x32_bf16 v[114:117], v[170:173], v[188:191], v[114:117]
	v_mfma_f32_16x16x32_bf16 v[106:109], v[180:183], v[188:191], v[106:109]
	v_mfma_f32_16x16x32_bf16 v[102:105], v[170:173], v[196:199], v[102:105]
	v_mfma_f32_16x16x32_bf16 v[98:101], v[180:183], v[196:199], v[98:101]
	v_mfma_f32_16x16x32_bf16 v[86:89], v[170:173], v[204:207], v[86:89]
	v_mfma_f32_16x16x32_bf16 v[82:85], v[180:183], v[204:207], v[82:85]
	v_mfma_f32_16x16x32_bf16 v[70:73], v[170:173], v[212:215], v[70:73]
	v_mfma_f32_16x16x32_bf16 v[66:69], v[180:183], v[212:215], v[66:69]
	v_mfma_f32_16x16x32_bf16 v[114:117], v[174:177], v[192:195], v[114:117]
	v_mfma_f32_16x16x32_bf16 v[106:109], v[184:187], v[192:195], v[106:109]
	v_mfma_f32_16x16x32_bf16 v[102:105], v[174:177], v[200:203], v[102:105]
	v_mfma_f32_16x16x32_bf16 v[98:101], v[184:187], v[200:203], v[98:101]
	v_mfma_f32_16x16x32_bf16 v[86:89], v[174:177], v[208:211], v[86:89]
	v_mfma_f32_16x16x32_bf16 v[82:85], v[184:187], v[208:211], v[82:85]
	v_mfma_f32_16x16x32_bf16 v[70:73], v[174:177], v[216:219], v[70:73]
	v_mfma_f32_16x16x32_bf16 v[66:69], v[184:187], v[216:219], v[66:69]
	s_setprio 0
.Lsplit7_mma2:
	s_barrier
	s_add_i32 s0, s33, s3
	v_lshl_add_u64 v[158:159], v[158:159], 0, s[16:17]
	s_mov_b32 m0, s0
	ds_read_b128 v[188:191], v165 offset:49152
	ds_read_b128 v[192:195], v165 offset:50176
	ds_read_b128 v[196:199], v165 offset:51200
	ds_read_b128 v[200:203], v165 offset:52224
	ds_read_b128 v[204:207], v165 offset:53248
	ds_read_b128 v[208:211], v165 offset:54272
	ds_read_b128 v[212:215], v165 offset:55296
	ds_read_b128 v[216:219], v165 offset:56320
	global_load_lds_dwordx4 v[158:159], off
	s_add_i32 m0, s0, 0x2000
	s_add_u32 s0, s30, 0x80080
	v_lshl_add_u64 v[158:159], v[220:221], 0, s[16:17]
	s_addc_u32 s1, s31, 0
	s_add_i32 s30, s52, s3
	global_load_lds_dwordx4 v[158:159], off
	v_lshl_add_u64 v[158:159], s[0:1], 0, v[138:139]
	s_mov_b32 m0, s30
	s_nop 0
	global_load_lds_dwordx4 v[158:159], off
	v_lshl_add_u64 v[158:159], s[0:1], 0, v[134:135]
	s_add_i32 m0, s30, 0x2000
	s_nop 0
	global_load_lds_dwordx4 v[158:159], off
	v_lshl_add_u64 v[158:159], v[222:223], 0, s[16:17]
	s_mov_b32 m0, s43
	s_nop 0
	global_load_lds_dwordx4 v[158:159], off
	v_lshl_add_u64 v[158:159], v[224:225], 0, s[16:17]
	s_mov_b32 m0, s56
	s_nop 0
	global_load_lds_dwordx4 v[158:159], off
	s_waitcnt vmcnt(8)
	s_waitcnt lgkmcnt(0)
	s_barrier
	s_cmp_eq_u32 s99, s98
	s_cbranch_scc1 .Lsplit7_mma3
	s_setprio 1
	s_waitcnt lgkmcnt(0)
	v_mfma_f32_16x16x32_bf16 v[62:65], v[130:133], v[188:191], v[62:65]
	v_mfma_f32_16x16x32_bf16 v[58:61], v[154:157], v[188:191], v[58:61]
	v_mfma_f32_16x16x32_bf16 v[46:49], v[130:133], v[196:199], v[46:49]
	v_mfma_f32_16x16x32_bf16 v[42:45], v[154:157], v[196:199], v[42:45]
	v_mfma_f32_16x16x32_bf16 v[30:33], v[130:133], v[204:207], v[30:33]
	v_mfma_f32_16x16x32_bf16 v[26:29], v[154:157], v[204:207], v[26:29]
	v_mfma_f32_16x16x32_bf16 v[14:17], v[130:133], v[212:215], v[14:17]
	v_mfma_f32_16x16x32_bf16 v[10:13], v[154:157], v[212:215], v[10:13]
	v_mfma_f32_16x16x32_bf16 v[62:65], v[150:153], v[192:195], v[62:65]
	v_mfma_f32_16x16x32_bf16 v[58:61], v[166:169], v[192:195], v[58:61]
	v_mfma_f32_16x16x32_bf16 v[46:49], v[150:153], v[200:203], v[46:49]
	v_mfma_f32_16x16x32_bf16 v[42:45], v[166:169], v[200:203], v[42:45]
	v_mfma_f32_16x16x32_bf16 v[30:33], v[150:153], v[208:211], v[30:33]
	v_mfma_f32_16x16x32_bf16 v[26:29], v[166:169], v[208:211], v[26:29]
	v_mfma_f32_16x16x32_bf16 v[14:17], v[150:153], v[216:219], v[14:17]
	v_mfma_f32_16x16x32_bf16 v[10:13], v[166:169], v[216:219], v[10:13]
	s_setprio 0
	s_setprio 1
	v_mfma_f32_16x16x32_bf16 v[54:57], v[170:173], v[188:191], v[54:57]
	v_mfma_f32_16x16x32_bf16 v[50:53], v[180:183], v[188:191], v[50:53]
	v_mfma_f32_16x16x32_bf16 v[38:41], v[170:173], v[196:199], v[38:41]
	v_mfma_f32_16x16x32_bf16 v[34:37], v[180:183], v[196:199], v[34:37]
	v_mfma_f32_16x16x32_bf16 v[22:25], v[170:173], v[204:207], v[22:25]
	v_mfma_f32_16x16x32_bf16 v[18:21], v[180:183], v[204:207], v[18:21]
	v_mfma_f32_16x16x32_bf16 v[6:9], v[170:173], v[212:215], v[6:9]
	v_mfma_f32_16x16x32_bf16 v[2:5], v[180:183], v[212:215], v[2:5]
	v_mfma_f32_16x16x32_bf16 v[54:57], v[174:177], v[192:195], v[54:57]
	v_mfma_f32_16x16x32_bf16 v[50:53], v[184:187], v[192:195], v[50:53]
	v_mfma_f32_16x16x32_bf16 v[38:41], v[174:177], v[200:203], v[38:41]
	v_mfma_f32_16x16x32_bf16 v[34:37], v[184:187], v[200:203], v[34:37]
	v_mfma_f32_16x16x32_bf16 v[22:25], v[174:177], v[208:211], v[22:25]
	v_mfma_f32_16x16x32_bf16 v[18:21], v[184:187], v[208:211], v[18:21]
	v_mfma_f32_16x16x32_bf16 v[6:9], v[174:177], v[216:219], v[6:9]
	v_mfma_f32_16x16x32_bf16 v[2:5], v[184:187], v[216:219], v[2:5]
	s_setprio 0
.Lsplit7_mma3:
	s_barrier
	s_add_i32 s67, s67, 2
	s_add_u32 s6, s6, 0x100
	s_addc_u32 s7, s7, 0
	s_add_u32 s65, s65, 0x100
	s_addc_u32 s66, s66, 0
	s_cmp_gt_u32 s67, 29
	s_cbranch_scc0 .LBB0_1458
	s_and_b64 vcc, exec, s[18:19]
	s_cbranch_vccz .LBB0_1461
	s_barrier
.LBB0_1461:
	s_cmp_eq_u32 s99, s98
	s_cbranch_scc0 .Lsplit7_run
	s_and_b64 vcc, exec, s[4:5]
	s_mov_b64 s[4:5], -1
	s_branch .Lsplit7_epi

.Lsplit7_epi:
	s_cbranch_vccnz .LBB0_1452
	s_andn2_b64 vcc, exec, s[14:15]
	s_cbranch_vccnz .LBB0_1451
	s_barrier
	s_branch .LBB0_1451

.LBB0_1465:
	s_cmp_gt_i32 s48, 32
	s_cselect_b32 s3, 32, 0
	s_cmp_lt_i32 s2, s3
	s_cbranch_scc1 .LBB0_1828
	s_add_i32 s0, 0, 0x200c8
	v_mov_b32_e32 v2, s0
	ds_read2_b64 v[2:5], v2 offset1:1
	s_sub_i32 s0, s2, s3
	v_lshl_add_u32 v92, s0, 3, v179
	s_movk_i32 s22, 0x4400
	v_cmp_gt_u32_e32 vcc, s22, v92
	s_waitcnt lgkmcnt(0)
	v_readfirstlane_b32 s14, v2
	v_readfirstlane_b32 s15, v3
	v_readfirstlane_b32 s4, v4
	v_readfirstlane_b32 s5, v5
	s_and_saveexec_b64 s[6:7], vcc
	s_cbranch_execz .LBB0_1473
	v_and_b32_e32 v34, 0x3f0, v1
	v_mov_b32_e32 v83, 0
	v_lshlrev_b32_e32 v82, 2, v34
	v_lshl_add_u64 v[36:37], s[14:15], 0, v[82:83]
	v_lshl_add_u64 v[38:39], s[4:5], 0, v[82:83]
	flat_load_dwordx4 v[2:5], v[36:37]
	flat_load_dwordx4 v[6:9], v[36:37] offset:16
	flat_load_dwordx4 v[10:13], v[38:39]
	flat_load_dwordx4 v[14:17], v[38:39] offset:16
	flat_load_dwordx4 v[18:21], v[36:37] offset:32
	flat_load_dwordx4 v[22:25], v[36:37] offset:48
	flat_load_dwordx4 v[26:29], v[38:39] offset:32
	flat_load_dwordx4 v[30:33], v[38:39] offset:48
	v_lshlrev_b32_e32 v82, 1, v34
	v_lshl_add_u64 v[36:37], s[46:47], 0, v[82:83]
	s_mov_b64 s[0:1], 0x1dd00000
	v_lshl_add_u64 v[84:85], v[36:37], 0, s[0:1]
	s_lshl_b32 s0, s3, 3
	s_sub_i32 s23, 0, s0
	s_lshl_b32 s0, s48, 4
	s_lshl_b32 s1, s3, 4
	s_sub_i32 s24, s0, s1
	s_lshl_b32 s0, s48, 3
	v_lshl_add_u32 v1, s2, 3, v179
	s_sub_i32 s25, s0, s1
	s_mov_b64 s[14:15], 0
	s_movk_i32 s26, 0x5200
	s_mov_b64 s[16:17], 0x1000
	s_mov_b64 s[18:19], 0x1800
	v_mov_b32_e32 v93, 0x3a27c5ac
	s_mov_b32 s27, 0x800000
	s_movk_i32 s28, 0x43ff
	v_mov_b64_e32 v[86:87], s[12:13]
	v_lshlrev_b32_e32 v82, 1, v34
	s_branch .LBB0_1469

.LBB0_1473:
	s_or_b64 exec, exec, s[6:7]
	s_cmp_eq_u32 s48, 0x100
	s_cbranch_scc1 .LBB0_1828
	s_cmp_gt_i32 s48, 32
	s_movk_i32 s99, 0x127f
	s_cselect_b32 s99, 0x1ff, s99
	s_mov_b32 s98, 0

.LBB0_1827:
	s_or_b64 exec, exec, s[24:25]
	s_cmp_eq_u32 s98, 8
	s_cbranch_scc1 .Ltr_ret8
	s_cmp_eq_u32 s98, 9
	s_cbranch_scc1 .Ltr_ret9
	s_cmp_eq_u32 s98, 4
	s_cbranch_scc1 .Ltr_tramp4
